# MoBA own block: each wave stages only its diagonal chunk, lower chunks read from the other waves' LDS staging areas (one barrier) instead of reloading
# baseline (speedup 1.0000x reference)
.LBB0_1952:
	s_waitcnt lgkmcnt(0)
	s_barrier
	v_add_u32_e32 v152, v231, v164
	ds_read_b128 v[48:51], v152
	ds_read_b128 v[52:55], v152 offset:32
	v_add_u32_e32 v153, v234, v228
	s_mov_b64 s[18:19], -1
	s_waitcnt vmcnt(3) lgkmcnt(1)
	v_mfma_f32_32x32x16_bf16 v[32:47], v[48:51], v[10:13], v[16:31]
	s_and_b64 vcc, exec, s[66:67]
	s_waitcnt vmcnt(2) lgkmcnt(0)
	v_mfma_f32_32x32x16_bf16 v[32:47], v[52:55], v[112:115], v[32:47]
	ds_read_b128 v[48:51], v152 offset:64
	ds_read_b128 v[52:55], v152 offset:96
	s_waitcnt vmcnt(1) lgkmcnt(1)
	v_mfma_f32_32x32x16_bf16 v[32:47], v[48:51], v[116:119], v[32:47]
	s_waitcnt vmcnt(0) lgkmcnt(0)
	v_mfma_f32_32x32x16_bf16 v[32:47], v[52:55], v[120:123], v[32:47]
	s_nop 11
	v_max_f32_e32 v1, v33, v33
	v_max_f32_e32 v14, v32, v32
	v_max_f32_e32 v1, v14, v1
	v_max3_f32 v1, v1, v34, v35
	v_max3_f32 v1, v1, v36, v37
	v_max3_f32 v1, v1, v38, v39
	v_max3_f32 v1, v1, v40, v41
	v_max3_f32 v1, v1, v42, v43
	v_max3_f32 v1, v1, v44, v45
	v_max3_f32 v1, v1, v46, v47
	v_mov_b32_e32 v14, v1
	s_nop 1
	v_permlane32_swap_b32_e32 v1, v14
	v_max_f32_e32 v14, v14, v14
	v_max_f32_e32 v1, v1, v1
	v_max_f32_e32 v15, v1, v14
	v_exp_f32_e64 v1, -v15
	v_sub_f32_e32 v14, v47, v15
	v_sub_f32_e32 v46, v46, v15
	v_sub_f32_e32 v45, v45, v15
	v_sub_f32_e32 v44, v44, v15
	v_sub_f32_e32 v43, v43, v15
	v_sub_f32_e32 v42, v42, v15
	v_sub_f32_e32 v41, v41, v15
	v_sub_f32_e32 v40, v40, v15
	v_sub_f32_e32 v39, v39, v15
	v_sub_f32_e32 v38, v38, v15
	v_sub_f32_e32 v37, v37, v15
	v_sub_f32_e32 v36, v36, v15
	v_sub_f32_e32 v35, v35, v15
	v_sub_f32_e32 v34, v34, v15
	v_sub_f32_e32 v33, v33, v15
	v_sub_f32_e32 v32, v32, v15
	v_exp_f32_e32 v53, v32
	v_exp_f32_e32 v52, v33
	v_exp_f32_e32 v55, v34
	v_exp_f32_e32 v54, v35
	v_exp_f32_e32 v57, v36
	v_exp_f32_e32 v56, v37
	v_exp_f32_e32 v59, v38
	v_exp_f32_e32 v58, v39
	v_exp_f32_e32 v61, v40
	v_exp_f32_e32 v60, v41
	v_exp_f32_e32 v63, v42
	v_exp_f32_e32 v62, v43
	v_exp_f32_e32 v97, v44
	v_exp_f32_e32 v96, v45
	v_exp_f32_e32 v99, v46
	v_exp_f32_e32 v98, v14
	v_cvt_pk_bf16_f32 v32, v53, v52
	v_cvt_pk_bf16_f32 v33, v55, v54
	v_cvt_pk_bf16_f32 v34, v57, v56
	v_cvt_pk_bf16_f32 v35, v59, v58
	v_cvt_pk_bf16_f32 v36, v61, v60
	v_cvt_pk_bf16_f32 v37, v63, v62
	v_cvt_pk_bf16_f32 v38, v97, v96
	v_cvt_pk_bf16_f32 v39, v99, v98
	ds_read_b64_tr_b16 v[40:41], v153 offset:4608
	ds_read_b64_tr_b16 v[42:43], v153 offset:5120
	v_mul_f32_e32 v64, 0, v1
	v_mov_b32_e32 v65, v64
	v_mov_b32_e32 v66, v64
	v_mov_b32_e32 v67, v64
	v_mov_b32_e32 v68, v64
	v_mov_b32_e32 v69, v64
	v_mov_b32_e32 v70, v64
	v_mov_b32_e32 v71, v64
	v_mov_b32_e32 v72, v64
	v_mov_b32_e32 v73, v64
	v_mov_b32_e32 v74, v64
	v_mov_b32_e32 v75, v64
	v_mov_b32_e32 v76, v64
	v_mov_b32_e32 v77, v64
	v_mov_b32_e32 v78, v64
	v_mov_b32_e32 v79, v64
	ds_read_b64_tr_b16 v[44:45], v153 offset:5632
	ds_read_b64_tr_b16 v[46:47], v153 offset:6144
	s_waitcnt lgkmcnt(2)
	v_mfma_f32_32x32x16_bf16 v[80:95], v[40:43], v[32:35], v[64:79]
	ds_read_b64_tr_b16 v[40:41], v153 offset:6656
	ds_read_b64_tr_b16 v[42:43], v153 offset:7168
	v_mov_b32_e32 v14, v64
	ds_read_b64_tr_b16 v[48:49], v153 offset:7680
	ds_read_b64_tr_b16 v[50:51], v153 offset:8192
	s_waitcnt lgkmcnt(0)
	s_waitcnt lgkmcnt(2)
	v_mfma_f32_32x32x16_bf16 v[64:79], v[40:43], v[32:35], v[64:79]
	v_add_f32_e64 v32, v52, 0
	v_add_f32_e64 v33, v53, 0
	v_add_f32_e64 v32, v54, v32
	v_add_f32_e64 v33, v55, v33
	v_add_f32_e64 v32, v56, v32
	v_add_f32_e64 v33, v57, v33
	v_pk_add_f32 v[32:33], v[58:59], v[32:33]
	v_mfma_f32_32x32x16_bf16 v[80:95], v[44:47], v[36:39], v[80:95]
	v_add_f32_e64 v32, v60, v32
	v_add_f32_e64 v33, v61, v33
	v_add_f32_e64 v32, v62, v32
	v_add_f32_e64 v33, v63, v33
	v_add_f32_e64 v32, v96, v32
	v_add_f32_e64 v33, v97, v33
	v_pk_add_f32 v[32:33], v[98:99], v[32:33]
	s_waitcnt lgkmcnt(0)
	v_mfma_f32_32x32x16_bf16 v[64:79], v[48:51], v[36:39], v[64:79]
	v_pk_add_f32 v[32:33], v[32:33], v[32:33] op_sel:[0,1] op_sel_hi:[1,0]
	s_nop 0
	v_mov_b32_e32 v33, v167
	v_pk_add_f32 v[148:149], v[14:15], v[32:33]
	s_cbranch_vccz .LBB0_1960
	s_nop 6
	v_mov_b64_e32 v[32:33], v[64:65]
	v_mov_b64_e32 v[48:49], v[80:81]
	v_add_u32_e32 v15, s91, v225
	s_mov_b32 s18, 1
	s_mov_b32 s19, 0
	v_mov_b64_e32 v[34:35], v[66:67]
	v_mov_b64_e32 v[36:37], v[68:69]
	v_mov_b64_e32 v[38:39], v[70:71]
	v_mov_b64_e32 v[40:41], v[72:73]
	v_mov_b64_e32 v[42:43], v[74:75]
	v_mov_b64_e32 v[44:45], v[76:77]
	v_mov_b64_e32 v[46:47], v[78:79]
	v_mov_b32_e32 v14, v148
	v_mov_b32_e32 v1, v149
	v_mov_b64_e32 v[50:51], v[82:83]
	v_mov_b64_e32 v[52:53], v[84:85]
	v_mov_b64_e32 v[54:55], v[86:87]
	v_mov_b64_e32 v[56:57], v[88:89]
	v_mov_b64_e32 v[58:59], v[90:91]
	v_mov_b64_e32 v[60:61], v[92:93]
	v_mov_b64_e32 v[62:63], v[94:95]
	s_branch .LBB0_1955

.LBB0_1955:
	v_subrev_u32_e32 v152, 0x4600, v152
	v_subrev_u32_e32 v153, 0x4600, v153
